# gl1 back end: removed the three store-drain vmcnt waits in front of its LDS reads (on top of the gl3 middle-section rewrite)
# speedup vs baseline: 1.0018x; 1.0018x over previous
; #define LAS __attribute__((address_space(3)))
; __device__ __forceinline__ void gl1_item(PREF p, int l, int item, bool valid, LAS unsigned char* pl, int sw, int lane) {
;     ...
;     if (valid) {
;         bf16x8 Ak[4][2]; f32x4 Dm[4];
; #pragma unroll
;         for (int mt = 0; mt < 4; ++mt) { Dm[mt] = *(const LAS f32x4*)(sD + mt * 16 + (lane >> 4) * 4);
; #pragma unroll
;             for (int ks = 0; ks < 2; ++ks) Ak[mt][ks] = *(const LAS bf16x8*)(sKt + (mt * 16 + (lane & 15)) * 72 + ks * 32 + (lane >> 4) * 8); }
;         bf16_t* So = (bf16_t*)GLS + (size_t)(seq * NCH + cj) * 8192;
; #pragma unroll 2
;         for (int nt = 0; nt < 8; ++nt) {
;             const bf16x8 B0 = *(const LAS bf16x8*)(sVt + (nt * 16 + (lane & 15)) * 72 + (lane >> 4) * 8), B1 = *(const LAS bf16x8*)(sVt + (nt * 16 + (lane & 15)) * 72 + 32 + (lane >> 4) * 8);
.LBB0_199:
	s_andn2_b64 vcc, exec, s[12:13]
	s_waitcnt lgkmcnt(0)
	s_barrier
	s_cbranch_vccnz .LBB0_183
	v_add_u32_e32 v36, s15, v67
	ds_read_b128 v[0:3], v65 offset:18432
	ds_read_b128 v[4:7], v65 offset:18496
	ds_read_b128 v[8:11], v36 offset:36864
	ds_read_b128 v[12:15], v36 offset:36928
	ds_read_b128 v[16:19], v65 offset:20736
	ds_read_b128 v[20:23], v65 offset:20800
	ds_read_b128 v[24:27], v65 offset:23040
	ds_read_b128 v[28:31], v65 offset:23104
	ds_read_b128 v[32:35], v36 offset:36992
	ds_read_b128 v[36:39], v36 offset:37056
	ds_read_b128 v[40:43], v69 offset:18432
	ds_read_b128 v[44:47], v69 offset:18496
	s_add_i32 s0, s38, s42
	s_mulk_i32 s0, 0x104
	s_add_i32 s0, s41, s0
	s_ashr_i32 s1, s0, 31
	s_lshl_b64 s[0:1], s[0:1], 14
	v_lshl_add_u64 v[60:61], v[58:59], 0, s[0:1]
	s_mov_b32 s0, 0
